# SB item prologue: the vmcnt(0) after the Q-fragment loads removed in both copies (the loop preheader's wait already covers them), so the Q round trip overlaps the first K/V LDS-DMA stages
# speedup vs baseline: 1.0013x; 1.0013x over previous
; DEV int otid() { int t = threadIdx.x; asm volatile("" : "+v"(t)); return t; }
; DEV void sb_block(const Params& p, int item) {
;   const int tidx = otid();
;   const int wave = __builtin_amdgcn_readfirstlane(tidx >> 6), lane = tidx & 63, l31 = lane & 31, hh = lane >> 5;
;   const int qb = 7 - (item >> 6), bh = item & 63, b = bh >> 4, h = bh & 15;
;   const int qt = 8 * qb + wave;
;   const bf16_t* sq = (const bf16_t*)(p.ws + OFF_SQ);
;   const bf16_t* sk = (const bf16_t*)(p.ws + OFF_SK);
;   const bf16_t* svT = (const bf16_t*)(p.ws + OFF_SVT);
;   const bf16_t* ssg = (const bf16_t*)(p.ws + OFF_SSG);
;   bf16_t* ob = (bf16_t*)(p.ws + OFF_OB);
;   const size_t row0 = (size_t)b * 2048;
;   bf16x8 qf[8];
;   {
;     const bf16_t* qp = sq + (row0 + qt * 32 + l31) * 2048 + h * 128 + 8 * hh;
; #pragma unroll
;     for (int s = 0; s < 8; ++s) qf[s] = ld16(qp + 16 * s);
;   }
;   f32x16 O[4];
; #pragma unroll
;   for (int d = 0; d < 4; ++d) for (int g = 0; g < 16; ++g) O[d][g] = 0.f;
;   float accp = 1.f;
;   const bf16_t* ksrc = sk + (row0 + (lane >> 4)) * 2048 + h * 128;
;   const bf16_t* vsrc = svT + ((size_t)(b * 2048 + h * 128 + (lane >> 3))) * 2048;
;     ...
;   const int KO0 = l31 * 256 + ((hh ^ (l31 & 15)) * 16);
;   const int VO0 = 16384 + l31 * 128 + ((hh ^ ((l31 >> 1) & 7)) * 16);
;   const int nsteps = 4 * qb + 4;
;   asm volatile("s_waitcnt vmcnt(0)" ::: "memory");
;   __syncthreads();
;   { const int j0 = nsteps - 1; SB_DMA(j0, 0); SB_DMA((j0 > 0 ? j0 - 1 : 0), 1); SB_DMA((j0 > 1 ? j0 - 2 : 0), 2); }
.LBB0_474:
	s_and_b64 vcc, exec, s[0:1]
	s_cbranch_vccz .LBB0_482
	v_mov_b32_e32 v201, v179
	s_add_i32 s0, s28, 0xffffff40
	s_mov_b32 s9, s93
	v_readfirstlane_b32 s1, v201
	s_ashr_i32 s89, s1, 6
	s_lshr_b32 s1, s0, 6
	s_xor_b32 s15, s1, 7
	s_lshl_b32 s74, s15, 3
	s_bfe_u32 s1, s28, 0x20004
	s_add_i32 s76, s89, s74
	v_writelane_b32 v252, s1, 6
	s_lshl_b32 s6, s1, 11
	s_lshl_b32 s1, s76, 5
	s_ashr_i32 s4, s1, 31
	s_add_u32 s1, s1, s6
	v_and_b32_e32 v203, 31, v201
	s_addc_u32 s4, s4, 0
	v_writelane_b32 v254, s1, 63
	v_or_b32_e32 v0, s1, v203
	v_writelane_b32 v254, s4, 62
	v_mov_b32_e32 v1, s4
	v_readlane_b32 s4, v253, 44
	s_lshl_b32 s0, s0, 7
	v_lshlrev_b64 v[0:1], 12, v[0:1]
	v_readlane_b32 s5, v253, 45
	s_and_b32 s0, s0, 0x780
	v_bfe_u32 v202, v201, 5, 1
	v_lshl_add_u64 v[0:1], s[4:5], 0, v[0:1]
	s_lshl_b32 s8, s0, 1
	v_lshl_add_u64 v[0:1], v[0:1], 0, s[8:9]
	v_lshlrev_b32_e32 v176, 4, v202
	v_lshl_add_u64 v[0:1], v[0:1], 0, v[176:177]
	global_load_dwordx4 v[128:131], v[0:1], off
	global_load_dwordx4 v[132:135], v[0:1], off offset:32
	global_load_dwordx4 v[136:139], v[0:1], off offset:64
	global_load_dwordx4 v[140:143], v[0:1], off offset:96
	global_load_dwordx4 v[144:147], v[0:1], off offset:128
	global_load_dwordx4 v[148:151], v[0:1], off offset:160
	global_load_dwordx4 v[152:155], v[0:1], off offset:192
	global_load_dwordx4 v[156:159], v[0:1], off offset:224
	s_or_b32 s0, s0, s6
	v_bfe_u32 v10, v201, 3, 3
	s_lshl_b32 s12, s15, 8
	v_or_b32_e32 v0, s0, v10
	v_readlane_b32 s0, v253, 50
	s_lshl_b32 s33, s89, 2
	s_or_b32 s92, s12, 0xc0
	v_and_b32_e32 v11, 63, v201
	v_lshlrev_b32_e32 v176, 12, v0
	v_readlane_b32 s1, v253, 51
	s_nop 0
	s_cmp_gt_i32 s89, 3
	v_lshlrev_b32_e32 v12, 4, v11
	v_lshl_add_u64 v[180:181], s[0:1], 0, v[176:177]
	s_cselect_b64 s[0:1], -1, 0
	v_lshl_add_u64 v[4:5], s[92:93], 1, v[180:181]
	v_add_u32_e32 v204, 0, v12
	s_mov_b64 s[4:5], -1
	s_and_b64 vcc, exec, s[0:1]
	s_barrier
	s_cbranch_vccz .LBB0_477
	s_add_i32 s7, s33, -16
	s_lshl_b32 s4, s7, 3
	v_or_b32_e32 v2, s4, v10
	v_lshrrev_b32_e32 v2, 1, v2
	v_xor_b32_e32 v2, v2, v201
	v_lshlrev_b32_e32 v2, 4, v2
	s_mov_b32 s5, s93
	v_and_b32_e32 v176, 0x70, v2
	v_lshl_add_u32 v2, s7, 10, v204
	s_lshl_b64 s[4:5], s[4:5], 12
	v_add_u32_e32 v2, 0x4000, v2
	v_lshl_add_u64 v[0:1], v[4:5], 0, s[4:5]
	v_readfirstlane_b32 s4, v2
	v_lshl_add_u64 v[0:1], v[0:1], 0, v[176:177]
	s_mov_b32 m0, s4
	s_mov_b64 s[4:5], 0
	global_load_lds_dwordx4 v[0:1], off

; DEV int otid() { int t = threadIdx.x; asm volatile("" : "+v"(t)); return t; }
; DEV void sb_block(const Params& p, int item) {
;   const int tidx = otid();
;   const int wave = __builtin_amdgcn_readfirstlane(tidx >> 6), lane = tidx & 63, l31 = lane & 31, hh = lane >> 5;
;   const int qb = 7 - (item >> 6), bh = item & 63, b = bh >> 4, h = bh & 15;
;   const int qt = 8 * qb + wave;
;   const bf16_t* sq = (const bf16_t*)(p.ws + OFF_SQ);
;   const bf16_t* sk = (const bf16_t*)(p.ws + OFF_SK);
;   const bf16_t* svT = (const bf16_t*)(p.ws + OFF_SVT);
;   const bf16_t* ssg = (const bf16_t*)(p.ws + OFF_SSG);
;   bf16_t* ob = (bf16_t*)(p.ws + OFF_OB);
;   const size_t row0 = (size_t)b * 2048;
;   bf16x8 qf[8];
;   {
;     const bf16_t* qp = sq + (row0 + qt * 32 + l31) * 2048 + h * 128 + 8 * hh;
; #pragma unroll
;     for (int s = 0; s < 8; ++s) qf[s] = ld16(qp + 16 * s);
;   }
;   f32x16 O[4];
; #pragma unroll
;   for (int d = 0; d < 4; ++d) for (int g = 0; g < 16; ++g) O[d][g] = 0.f;
;   float accp = 1.f;
;   const bf16_t* ksrc = sk + (row0 + (lane >> 4)) * 2048 + h * 128;
;   const bf16_t* vsrc = svT + ((size_t)(b * 2048 + h * 128 + (lane >> 3))) * 2048;
;     ...
;   const int KO0 = l31 * 256 + ((hh ^ (l31 & 15)) * 16);
;   const int VO0 = 16384 + l31 * 128 + ((hh ^ ((l31 >> 1) & 7)) * 16);
;   const int nsteps = 4 * qb + 4;
;   asm volatile("s_waitcnt vmcnt(0)" ::: "memory");
;   __syncthreads();
;   { const int j0 = nsteps - 1; SB_DMA(j0, 0); SB_DMA((j0 > 0 ? j0 - 1 : 0), 1); SB_DMA((j0 > 1 ? j0 - 2 : 0), 2); }
.LBB0_484:
	v_mov_b32_e32 v201, v179
	s_sub_i32 s0, s28, 64
	v_readlane_b32 s6, v253, 44
	v_readfirstlane_b32 s1, v201
	s_ashr_i32 s89, s1, 6
	s_lshr_b32 s1, s0, 6
	s_xor_b32 s14, s1, 7
	s_lshl_b32 s74, s14, 3
	s_bfe_u32 s1, s28, 0x20004
	s_add_i32 s75, s89, s74
	v_writelane_b32 v254, s1, 61
	s_lshl_b32 s4, s1, 11
	s_lshl_b32 s1, s75, 5
	s_ashr_i32 s5, s1, 31
	s_add_u32 s1, s1, s4
	v_and_b32_e32 v203, 31, v201
	s_addc_u32 s5, s5, 0
	v_or_b32_e32 v0, s1, v203
	v_mov_b32_e32 v1, s5
	s_lshl_b32 s0, s0, 7
	v_lshlrev_b64 v[0:1], 12, v[0:1]
	v_readlane_b32 s7, v253, 45
	s_and_b32 s0, s0, 0x780
	v_bfe_u32 v202, v201, 5, 1
	v_lshl_add_u64 v[0:1], s[6:7], 0, v[0:1]
	s_lshl_b32 s6, s0, 1
	s_mov_b32 s7, s93
	v_lshl_add_u64 v[0:1], v[0:1], 0, s[6:7]
	v_lshlrev_b32_e32 v176, 4, v202
	v_lshl_add_u64 v[0:1], v[0:1], 0, v[176:177]
	global_load_dwordx4 v[128:131], v[0:1], off
	global_load_dwordx4 v[132:135], v[0:1], off offset:32
	global_load_dwordx4 v[136:139], v[0:1], off offset:64
	global_load_dwordx4 v[140:143], v[0:1], off offset:96
	global_load_dwordx4 v[144:147], v[0:1], off offset:128
	global_load_dwordx4 v[148:151], v[0:1], off offset:160
	global_load_dwordx4 v[152:155], v[0:1], off offset:192
	global_load_dwordx4 v[156:159], v[0:1], off offset:224
	s_or_b32 s0, s0, s4
	v_bfe_u32 v10, v201, 3, 3
	s_lshl_b32 s12, s14, 8
	v_writelane_b32 v254, s1, 62
	v_or_b32_e32 v0, s0, v10
	v_readlane_b32 s0, v253, 50
	s_lshl_b32 s33, s89, 2
	s_or_b32 s92, s12, 0xc0
	v_and_b32_e32 v11, 63, v201
	v_lshlrev_b32_e32 v176, 12, v0
	v_readlane_b32 s1, v253, 51
	s_nop 0
	s_cmp_gt_i32 s89, 3
	v_lshlrev_b32_e32 v12, 4, v11
	v_lshl_add_u64 v[180:181], s[0:1], 0, v[176:177]
	s_cselect_b64 s[90:91], -1, 0
	v_writelane_b32 v254, s5, 63
	v_lshl_add_u64 v[4:5], s[92:93], 1, v[180:181]
	v_add_u32_e32 v204, 0, v12
	s_mov_b64 s[0:1], -1
	s_and_b64 vcc, exec, s[90:91]
	s_barrier
	s_cbranch_vccz .LBB0_486
	s_add_i32 s5, s33, -16
	s_lshl_b32 s0, s5, 3
	v_or_b32_e32 v2, s0, v10
	v_lshrrev_b32_e32 v2, 1, v2
	v_xor_b32_e32 v2, v2, v201
	v_lshlrev_b32_e32 v2, 4, v2
	s_mov_b32 s1, s93
	v_and_b32_e32 v176, 0x70, v2
	v_lshl_add_u32 v2, s5, 10, v204
	s_lshl_b64 s[0:1], s[0:1], 12
	v_add_u32_e32 v2, 0x4000, v2
	v_lshl_add_u64 v[0:1], v[4:5], 0, s[0:1]
	v_readfirstlane_b32 s0, v2
	v_lshl_add_u64 v[0:1], v[0:1], 0, v[176:177]
	s_mov_b32 m0, s0
	s_mov_b64 s[0:1], 0
	global_load_lds_dwordx4 v[0:1], off
